# lever 8 (MFMA shadow fill): scan S3 waves 0-3 compute silu(z) between the 16 MFMAs; epilogue reduced to fma/mul/cvt/store
# baseline (speedup 1.0000x reference)
; #define MFMA(a, b, c) __builtin_amdgcn_mfma_f32_32x32x16_bf16((a), (b), (c), 0, 0, 0)
; DI void ssd_scan_phase(bf16_t* P, const bf16_t* BT, const bf16_t* Cc, const bf16_t* CB, const float* dt, const float* acs,
;                        const float* cw, const float* cb, const float* Dp, char* lds, bool dry, int mode, float* Sbuf) {
;     ...
;       if (wave < 4) {
;        if (mode == 0) {
;         const int lt = wave;
;         f32x16 ad, ao;
; #pragma unroll
;         for (int i = 0; i < 16; ++i) { ad[i] = 0.f; ao[i] = 0.f; }
;         const char* stb = sSt + (c & 1) * 8192;
; #pragma unroll
;         for (int kk = 0; kk < 8; ++kk) {
;           const bf16x8 yf = *(const bf16x8*)(sCBL + swz128(32 * lt + lq, 2 * kk + hq));
;           const bf16x8 xf = *(const bf16x8*)(sXdt + swz128(lq, 2 * kk + hq));
;           ad = MFMA(xf, yf, ad);
;           const bf16x8 yf2 = *(const bf16x8*)(sC + swz128(32 * lt + lq, 2 * kk + hq));
;           const bf16x8 xf2 = *(const bf16x8*)(stb + swz128(lq, 2 * kk + hq));
;           ao = MFMA(xf2, yf2, ao);
;         }
.LBB0_1101:
	s_waitcnt lgkmcnt(0)
	s_barrier
	v_mov_b32_e32 v197, v133
	v_mov_b32_e32 v174, v175
	s_and_saveexec_b64 s[80:81], s[40:41]
	s_xor_b64 s[80:81], exec, s[80:81]
	s_cbranch_execz .LBB0_1107
	s_and_b64 vcc, exec, s[56:57]
	s_cbranch_vccnz .LBB0_1106
	s_andn2_b64 vcc, exec, s[82:83]
	v_bitop3_b32 v20, v174, v197, 15 bitop3:0x6c
	v_lshlrev_b32_e32 v199, 8, v174
	v_lshlrev_b32_e32 v24, 4, v20
	v_add_lshl_u32 v198, v174, v183, 8
	s_add_i32 s91, 0, 0x18000
	s_lshl_b32 s90, s90, 13
	s_add_i32 s90, s90, 0
	s_add_i32 s90, s90, 0x1c000
	v_add_u32_e32 v250, v24, v198
	v_add_u32_e32 v251, v24, v199
	v_add_u32_e32 v230, s90, v251
	v_add_u32_e32 v251, s91, v251
	ds_read_b128 v[20:23], v250
	ds_read_b128 v[24:27], v251
	ds_read_b128 v[36:39], v250 offset:32768
	ds_read_b128 v[40:43], v230
	v_xor_b32_e32 v231, 0x20, v250
	ds_read_b128 v[222:225], v231
	v_xor_b32_e32 v231, 0x20, v251
	ds_read_b128 v[226:229], v231
	v_xor_b32_e32 v231, 0x20, v250
	ds_read_b128 v[234:237], v231 offset:32768
	v_xor_b32_e32 v231, 0x20, v230
	ds_read_b128 v[238:241], v231
	v_xor_b32_e32 v231, 0x40, v250
	ds_read_b128 v[242:245], v231
	v_xor_b32_e32 v231, 0x40, v251
	ds_read_b128 v[246:249], v231
	s_waitcnt lgkmcnt(8)
	v_mfma_f32_32x32x16_bf16 v[20:35], v[24:27], v[20:23], 0
	v_lshlrev_b32_e32 v4, 16, v158
	v_and_b32_e32 v5, 0xffff0000, v158
	v_lshlrev_b32_e32 v6, 16, v159
	v_and_b32_e32 v7, 0xffff0000, v159
	v_mul_f32_e32 v96, 0xbfb8aa3b, v4
	v_mul_f32_e32 v97, 0xbfb8aa3b, v5
	s_waitcnt lgkmcnt(6)
	v_mfma_f32_32x32x16_bf16 v[36:51], v[40:43], v[36:39], 0
	v_mul_f32_e32 v98, 0xbfb8aa3b, v6
	v_mul_f32_e32 v99, 0xbfb8aa3b, v7
	v_exp_f32_e32 v96, v96
	v_exp_f32_e32 v97, v97
	v_exp_f32_e32 v98, v98
	v_exp_f32_e32 v99, v99
	s_waitcnt lgkmcnt(4)
	v_mfma_f32_32x32x16_bf16 v[20:35], v[226:229], v[222:225], v[20:35]
	v_add_f32_e32 v96, 1.0, v96
	v_add_f32_e32 v97, 1.0, v97
	v_add_f32_e32 v98, 1.0, v98
	v_add_f32_e32 v99, 1.0, v99
	v_rcp_f32_e32 v96, v96
	v_xor_b32_e32 v231, 0x40, v250
	ds_read_b128 v[222:225], v231 offset:32768
	v_xor_b32_e32 v231, 0x40, v230
	ds_read_b128 v[226:229], v231
	s_waitcnt lgkmcnt(4)
	v_mfma_f32_32x32x16_bf16 v[36:51], v[238:241], v[234:237], v[36:51]
	v_rcp_f32_e32 v97, v97
	v_rcp_f32_e32 v98, v98
	v_rcp_f32_e32 v99, v99
	v_pk_mul_f32 v[4:5], v[96:97], v[4:5]
	v_pk_mul_f32 v[6:7], v[98:99], v[6:7]
	v_xor_b32_e32 v231, 0x60, v250
	ds_read_b128 v[234:237], v231
	v_xor_b32_e32 v231, 0x60, v251
	ds_read_b128 v[238:241], v231
	s_waitcnt lgkmcnt(4)
	v_mfma_f32_32x32x16_bf16 v[20:35], v[246:249], v[242:245], v[20:35]
	v_lshlrev_b32_e32 v8, 16, v160
	v_and_b32_e32 v9, 0xffff0000, v160
	v_lshlrev_b32_e32 v10, 16, v161
	v_and_b32_e32 v11, 0xffff0000, v161
	v_mul_f32_e32 v96, 0xbfb8aa3b, v8
	v_mul_f32_e32 v97, 0xbfb8aa3b, v9
	v_xor_b32_e32 v231, 0x60, v250
	ds_read_b128 v[242:245], v231 offset:32768
	v_xor_b32_e32 v231, 0x60, v230
	ds_read_b128 v[246:249], v231
	s_waitcnt lgkmcnt(4)
	v_mfma_f32_32x32x16_bf16 v[36:51], v[226:229], v[222:225], v[36:51]
	v_mul_f32_e32 v98, 0xbfb8aa3b, v10
	v_mul_f32_e32 v99, 0xbfb8aa3b, v11
	v_exp_f32_e32 v96, v96
	v_exp_f32_e32 v97, v97
	v_exp_f32_e32 v98, v98
	v_exp_f32_e32 v99, v99
	v_xor_b32_e32 v231, 0x80, v250
	ds_read_b128 v[222:225], v231
	v_xor_b32_e32 v231, 0x80, v251
	ds_read_b128 v[226:229], v231
	s_waitcnt lgkmcnt(4)
	v_mfma_f32_32x32x16_bf16 v[20:35], v[238:241], v[234:237], v[20:35]
	v_add_f32_e32 v96, 1.0, v96
	v_add_f32_e32 v97, 1.0, v97
	v_add_f32_e32 v98, 1.0, v98
	v_add_f32_e32 v99, 1.0, v99
	v_rcp_f32_e32 v96, v96
	v_xor_b32_e32 v231, 0x80, v250
	ds_read_b128 v[234:237], v231 offset:32768
	v_xor_b32_e32 v231, 0x80, v230
	ds_read_b128 v[238:241], v231
	s_waitcnt lgkmcnt(4)
	v_mfma_f32_32x32x16_bf16 v[36:51], v[246:249], v[242:245], v[36:51]
	v_rcp_f32_e32 v97, v97
	v_rcp_f32_e32 v98, v98
	v_rcp_f32_e32 v99, v99
	v_pk_mul_f32 v[8:9], v[96:97], v[8:9]
	v_pk_mul_f32 v[10:11], v[98:99], v[10:11]
	v_xor_b32_e32 v231, 0xa0, v250
	ds_read_b128 v[242:245], v231
	v_xor_b32_e32 v231, 0xa0, v251
	ds_read_b128 v[246:249], v231
	s_waitcnt lgkmcnt(4)
	v_mfma_f32_32x32x16_bf16 v[20:35], v[226:229], v[222:225], v[20:35]
	v_lshlrev_b32_e32 v12, 16, v162
	v_and_b32_e32 v13, 0xffff0000, v162
	v_lshlrev_b32_e32 v14, 16, v163
	v_and_b32_e32 v15, 0xffff0000, v163
	v_mul_f32_e32 v96, 0xbfb8aa3b, v12
	v_mul_f32_e32 v97, 0xbfb8aa3b, v13
	v_xor_b32_e32 v231, 0xa0, v250
	ds_read_b128 v[222:225], v231 offset:32768
	v_xor_b32_e32 v231, 0xa0, v230
	ds_read_b128 v[226:229], v231
	s_waitcnt lgkmcnt(4)
	v_mfma_f32_32x32x16_bf16 v[36:51], v[238:241], v[234:237], v[36:51]
	v_mul_f32_e32 v98, 0xbfb8aa3b, v14
	v_mul_f32_e32 v99, 0xbfb8aa3b, v15
	v_exp_f32_e32 v96, v96
	v_exp_f32_e32 v97, v97
	v_exp_f32_e32 v98, v98
	v_exp_f32_e32 v99, v99
	v_xor_b32_e32 v231, 0xc0, v250
	ds_read_b128 v[234:237], v231
	v_xor_b32_e32 v231, 0xc0, v251
	ds_read_b128 v[238:241], v231
	s_waitcnt lgkmcnt(4)
; #define MFMA(a, b, c) __builtin_amdgcn_mfma_f32_32x32x16_bf16((a), (b), (c), 0, 0, 0)
; DI unsigned pk2(float lo, float hi) { f32x2 v = {lo, hi}; bf2_t r = __builtin_convertvector(v, bf2_t); return __builtin_bit_cast(unsigned, r); }
; DI float bflo(unsigned u) { return __uint_as_float(u << 16); }
; DI float bfhi(unsigned u) { return __uint_as_float(u & 0xffff0000u); }
; DI float silu(float x) { return x * __builtin_amdgcn_rcpf(1.f + __expf(-x)); }
; DI void ssd_scan_phase(bf16_t* P, const bf16_t* BT, const bf16_t* Cc, const bf16_t* CB, const float* dt, const float* acs,
;                        const float* cw, const float* cb, const float* Dp, char* lds, bool dry, int mode, float* Sbuf) {
;     ...
;         for (int kk = 0; kk < 8; ++kk) {
;           const bf16x8 yf = *(const bf16x8*)(sCBL + swz128(32 * lt + lq, 2 * kk + hq));
;           const bf16x8 xf = *(const bf16x8*)(sXdt + swz128(lq, 2 * kk + hq));
;           ad = MFMA(xf, yf, ad);
;           const bf16x8 yf2 = *(const bf16x8*)(sC + swz128(32 * lt + lq, 2 * kk + hq));
;           const bf16x8 xf2 = *(const bf16x8*)(stb + swz128(lq, 2 * kk + hq));
;           ao = MFMA(xf2, yf2, ao);
;         }
;         const int l = 32 * lt + l31;
;         const float eo = __expf(cAcs[l]);
;         bf16_t* Zq = P + t0 * 5120 + pcol;
; #pragma unroll
;         for (int gi = 0; gi < 4; ++gi) {
;           const int p0 = 8 * gi + 4 * h;
;           const u32x2 xsv = *(const u32x2*)(sXs + l * 80 + p0 * 2);
;           const u32x2 zv = cz[gi];
;           const float xs0 = bflo(xsv[0]), xs1 = bfhi(xsv[0]), xs2 = bflo(xsv[1]), xs3 = bfhi(xsv[1]);
;           const float z0 = bflo(zv[0]), z1 = bfhi(zv[0]), z2 = bflo(zv[1]), z3 = bfhi(zv[1]);
;           const float y0 = (ad[4 * gi] + eo * ao[4 * gi] + Dh * xs0) * silu(z0);
;           const float y1 = (ad[4 * gi + 1] + eo * ao[4 * gi + 1] + Dh * xs1) * silu(z1);
;           const float y2 = (ad[4 * gi + 2] + eo * ao[4 * gi + 2] + Dh * xs2) * silu(z2);
;           const float y3 = (ad[4 * gi + 3] + eo * ao[4 * gi + 3] + Dh * xs3) * silu(z3);
;           u32x2 ov; ov[0] = pk2(y0, y1); ov[1] = pk2(y2, y3);
;           if (!dry) *(u32x2*)(Zq + zoff + 8 * gi) = ov;
;         }
;         if (c + 1 < c1) {
; #pragma unroll
;           for (int gi = 0; gi < 4; ++gi) cz[gi] = *(const u32x2*)(Zq + 128 * 5120 + zoff + 8 * gi);
;         }
	v_mfma_f32_32x32x16_bf16 v[20:35], v[246:249], v[242:245], v[20:35]
	v_add_f32_e32 v96, 1.0, v96
	v_add_f32_e32 v97, 1.0, v97
	v_add_f32_e32 v98, 1.0, v98
	v_add_f32_e32 v99, 1.0, v99
	v_rcp_f32_e32 v96, v96
	v_xor_b32_e32 v231, 0xc0, v250
	ds_read_b128 v[242:245], v231 offset:32768
	v_xor_b32_e32 v231, 0xc0, v230
	ds_read_b128 v[246:249], v231
	s_waitcnt lgkmcnt(4)
	v_mfma_f32_32x32x16_bf16 v[36:51], v[226:229], v[222:225], v[36:51]
	v_rcp_f32_e32 v97, v97
	v_rcp_f32_e32 v98, v98
	v_rcp_f32_e32 v99, v99
	v_pk_mul_f32 v[12:13], v[96:97], v[12:13]
	v_pk_mul_f32 v[14:15], v[98:99], v[14:15]
	v_xor_b32_e32 v231, 0xe0, v250
	ds_read_b128 v[222:225], v231
	v_xor_b32_e32 v231, 0xe0, v251
	ds_read_b128 v[226:229], v231
	s_waitcnt lgkmcnt(4)
	v_mfma_f32_32x32x16_bf16 v[20:35], v[238:241], v[234:237], v[20:35]
	v_lshlrev_b32_e32 v16, 16, v2
	v_and_b32_e32 v17, 0xffff0000, v2
	v_lshlrev_b32_e32 v18, 16, v3
	v_and_b32_e32 v19, 0xffff0000, v3
	v_mul_f32_e32 v96, 0xbfb8aa3b, v16
	v_mul_f32_e32 v97, 0xbfb8aa3b, v17
	v_xor_b32_e32 v231, 0xe0, v250
	ds_read_b128 v[234:237], v231 offset:32768
	v_xor_b32_e32 v231, 0xe0, v230
	ds_read_b128 v[238:241], v231
	v_lshl_add_u32 v174, v187, 2, s88
	ds_read_b32 v174, v174
	v_mov_b64_e32 v[198:199], s[72:73]
	v_mad_u64_u32 v[198:199], s[90:91], v172, s96, v[198:199]
	v_mad_i32_i24 v199, v173, s96, v199
	v_lshl_add_u64 v[172:173], v[198:199], 0, v[0:1]
	s_waitcnt lgkmcnt(5)
	v_mfma_f32_32x32x16_bf16 v[36:51], v[246:249], v[242:245], v[36:51]
	v_mul_f32_e32 v98, 0xbfb8aa3b, v18
	v_mul_f32_e32 v99, 0xbfb8aa3b, v19
	v_exp_f32_e32 v96, v96
	v_exp_f32_e32 v97, v97
	v_exp_f32_e32 v98, v98
	v_exp_f32_e32 v99, v99
	s_waitcnt lgkmcnt(3)
	v_mfma_f32_32x32x16_bf16 v[20:35], v[226:229], v[222:225], v[20:35]
	v_add_f32_e32 v96, 1.0, v96
	v_add_f32_e32 v97, 1.0, v97
	v_add_f32_e32 v98, 1.0, v98
	v_add_f32_e32 v99, 1.0, v99
	v_rcp_f32_e32 v96, v96
	s_waitcnt lgkmcnt(0)
	v_mul_f32_e32 v174, 0x3fb8aa3b, v174
	v_mfma_f32_32x32x16_bf16 v[36:51], v[238:241], v[234:237], v[36:51]
	v_rcp_f32_e32 v97, v97
	v_rcp_f32_e32 v98, v98
	v_rcp_f32_e32 v99, v99
	v_pk_mul_f32 v[16:17], v[96:97], v[16:17]
	v_pk_mul_f32 v[18:19], v[98:99], v[18:19]
	v_exp_f32_e32 v174, v174
	ds_read2_b64 v[222:225], v193 offset1:2
	ds_read2_b64 v[226:229], v193 offset0:4 offset1:6
	s_nop 7
	s_nop 7
	v_pk_fma_f32 v[20:21], v[36:37], v[174:175], v[20:21] op_sel_hi:[1,0,1]
	v_pk_fma_f32 v[22:23], v[38:39], v[174:175], v[22:23] op_sel_hi:[1,0,1]
	v_pk_fma_f32 v[24:25], v[40:41], v[174:175], v[24:25] op_sel_hi:[1,0,1]
	v_pk_fma_f32 v[26:27], v[42:43], v[174:175], v[26:27] op_sel_hi:[1,0,1]
	v_pk_fma_f32 v[28:29], v[44:45], v[174:175], v[28:29] op_sel_hi:[1,0,1]
	v_pk_fma_f32 v[30:31], v[46:47], v[174:175], v[30:31] op_sel_hi:[1,0,1]
	v_pk_fma_f32 v[32:33], v[48:49], v[174:175], v[32:33] op_sel_hi:[1,0,1]
	v_pk_fma_f32 v[34:35], v[50:51], v[174:175], v[34:35] op_sel_hi:[1,0,1]
	s_waitcnt lgkmcnt(0)
	v_lshlrev_b32_e32 v36, 16, v222
	v_and_b32_e32 v37, 0xffff0000, v222
	v_lshlrev_b32_e32 v38, 16, v223
	v_and_b32_e32 v39, 0xffff0000, v223
	v_pk_fma_f32 v[20:21], v[156:157], v[36:37], v[20:21]
	v_pk_fma_f32 v[22:23], v[156:157], v[38:39], v[22:23]
	v_pk_mul_f32 v[20:21], v[4:5], v[20:21]
	v_pk_mul_f32 v[22:23], v[6:7], v[22:23]
	v_cvt_pk_bf16_f32 v20, v20, v21
	v_cvt_pk_bf16_f32 v21, v22, v23
	global_store_dwordx2 v[172:173], v[20:21], off
	v_lshlrev_b32_e32 v40, 16, v224
	v_and_b32_e32 v41, 0xffff0000, v224
	v_lshlrev_b32_e32 v42, 16, v225
	v_and_b32_e32 v43, 0xffff0000, v225
	v_pk_fma_f32 v[24:25], v[156:157], v[40:41], v[24:25]
	v_pk_fma_f32 v[26:27], v[156:157], v[42:43], v[26:27]
	v_pk_mul_f32 v[24:25], v[8:9], v[24:25]
	v_pk_mul_f32 v[26:27], v[10:11], v[26:27]
	v_cvt_pk_bf16_f32 v24, v24, v25
	v_cvt_pk_bf16_f32 v25, v26, v27
	global_store_dwordx2 v[172:173], v[24:25], off offset:16
	v_lshlrev_b32_e32 v36, 16, v226
	v_and_b32_e32 v37, 0xffff0000, v226
	v_lshlrev_b32_e32 v38, 16, v227
	v_and_b32_e32 v39, 0xffff0000, v227
	v_pk_fma_f32 v[28:29], v[156:157], v[36:37], v[28:29]
	v_pk_fma_f32 v[30:31], v[156:157], v[38:39], v[30:31]
	v_pk_mul_f32 v[28:29], v[12:13], v[28:29]
	v_pk_mul_f32 v[30:31], v[14:15], v[30:31]
	v_cvt_pk_bf16_f32 v28, v28, v29
	v_cvt_pk_bf16_f32 v29, v30, v31
	global_store_dwordx2 v[172:173], v[28:29], off offset:32
	v_lshlrev_b32_e32 v40, 16, v228
	v_and_b32_e32 v41, 0xffff0000, v228
	v_lshlrev_b32_e32 v42, 16, v229
	v_and_b32_e32 v43, 0xffff0000, v229
	v_pk_fma_f32 v[32:33], v[156:157], v[40:41], v[32:33]
	v_pk_fma_f32 v[34:35], v[156:157], v[42:43], v[34:35]
	v_pk_mul_f32 v[32:33], v[16:17], v[32:33]
	v_pk_mul_f32 v[34:35], v[18:19], v[34:35]
	v_cvt_pk_bf16_f32 v32, v32, v33
	v_cvt_pk_bf16_f32 v33, v34, v35
	global_store_dwordx2 v[172:173], v[32:33], off offset:48
	s_cbranch_vccnz .LBB0_1105
	s_mov_b64 s[82:83], 0x140000
	v_add_co_u32_e32 v20, vcc, 0x140000, v172
	v_lshl_add_u64 v[2:3], v[172:173], 0, s[82:83]
	s_nop 0
	v_addc_co_u32_e32 v21, vcc, 0, v173, vcc
	global_load_dwordx2 v[158:159], v[20:21], off
	global_load_dwordx2 v[160:161], v[2:3], off offset:16
	global_load_dwordx2 v[162:163], v[2:3], off offset:32
	s_nop 0
	global_load_dwordx2 v[2:3], v[2:3], off offset:48
